# static s_setprio 1 for waves 0-3 also during the two LayerNorm phases (LN1 reset at exit; LN2 runs to kernel end)
# baseline (speedup 1.0000x reference)
.LBB0_1739:
	s_or_b64 exec, exec, s[4:5]
	v_mov_b32_e32 v0, v228
	s_barrier
	v_readlane_b32 s5, v251, 2
	v_readfirstlane_b32 s4, v0
	s_ashr_i32 s4, s4, 6
	s_add_i32 s20, s4, s5
	s_add_u32 s16, s90, 0x199c0800
	s_addc_u32 s17, s91, 0
	s_add_u32 s12, s90, 0x38bb0800
	s_addc_u32 s13, s91, 0
	s_cmp_gt_i32 s20, 0x100ff
	s_cbranch_scc1 .LBB0_1752
	v_and_b32_e32 v4, 63, v0
	v_mov_b32_e32 v32, 0
	v_lshlrev_b32_e32 v0, 4, v4
	v_mov_b32_e32 v1, v32
	v_lshlrev_b32_e32 v2, 3, v4
	v_mov_b32_e32 v3, v32
	v_cmp_gt_u32_e64 s[4:5], 16, v4
	v_lshl_add_u64 v[34:35], s[0:1], 0, v[0:1]
	v_lshl_add_u64 v[36:37], s[14:15], 0, v[2:3]
	v_cmp_eq_u32_e64 s[6:7], 0, v4
	v_lshl_add_u64 v[38:39], s[42:43], 0, v[0:1]
	v_lshl_add_u64 v[40:41], s[44:45], 0, v[0:1]
	v_lshl_add_u64 v[42:43], s[16:17], 0, v[2:3]
	s_mov_b32 s24, 0x3a800000
	s_mov_b32 s25, 0xf800000
	v_mov_b32_e32 v48, 0x260
	v_readfirstlane_b32 s8, v228
	s_cmpk_lt_u32 s8, 0x100
	s_cbranch_scc0 .Lln1prio_skip
	s_setprio 1
.Lln1prio_skip:
	global_load_dwordx4 v[60:63], v[38:39], off
	global_load_dwordx4 v[76:79], v[40:41], off
	global_load_dwordx4 v[64:67], v[38:39], off offset:1024
	global_load_dwordx4 v[80:83], v[40:41], off offset:1024
	global_load_dwordx4 v[68:71], v[38:39], off offset:2048
	global_load_dwordx4 v[84:87], v[40:41], off offset:2048
	global_load_dwordx4 v[72:75], v[38:39], off offset:3072
	global_load_dwordx4 v[88:91], v[40:41], off offset:3072
	v_mov_b32_e32 v132, 0
	v_mov_b32_e32 v133, 0
	v_mov_b32_e32 v134, 0
	v_mov_b32_e32 v135, 0
	s_add_i32 s14, s20, s76
	s_cmp_lt_i32 s14, 0x10100
	s_cselect_b32 s14, s14, s20
	s_ashr_i32 s21, s20, 31
	s_ashr_i32 s15, s14, 31
	s_lshl_b64 s[8:9], s[20:21], 12
	v_lshl_add_u64 v[136:137], v[34:35], 0, s[8:9]
	s_lshl_b64 s[8:9], s[14:15], 12
	v_lshl_add_u64 v[138:139], v[34:35], 0, s[8:9]
	s_lshl_b64 s[8:9], s[20:21], 7
	v_lshl_add_u64 v[144:145], v[36:37], 0, s[8:9]
	s_lshl_b64 s[8:9], s[14:15], 7
	v_lshl_add_u64 v[146:147], v[36:37], 0, s[8:9]
	s_and_saveexec_b64 s[8:9], s[4:5]
	global_load_dwordx2 v[132:133], v[144:145], off
	global_load_dwordx2 v[134:135], v[146:147], off
	s_mov_b64 exec, s[8:9]
	global_load_dwordx4 v[100:103], v[136:137], off nt
	global_load_dwordx4 v[104:107], v[136:137], off offset:1024 nt
	global_load_dwordx4 v[108:111], v[136:137], off offset:2048 nt
	global_load_dwordx4 v[112:115], v[136:137], off offset:3072 nt
	global_load_dwordx4 v[116:119], v[138:139], off nt
	global_load_dwordx4 v[120:123], v[138:139], off offset:1024 nt
	global_load_dwordx4 v[124:127], v[138:139], off offset:2048 nt
	global_load_dwordx4 v[128:131], v[138:139], off offset:3072 nt
	s_waitcnt vmcnt(0)

.LBB0_1752:
	s_setprio 0
	s_barrier
	s_and_saveexec_b64 s[4:5], s[68:69]
	s_cbranch_execz .LBB0_1762
	v_readlane_b32 s6, v251, 0
	v_readlane_b32 s7, v251, 1
	buffer_wbl2 sc1
	s_waitcnt vmcnt(0)
	s_load_dwordx2 s[6:7], s[6:7], 0x58
	v_mov_b32_e32 v2, 0
	s_mov_b64 s[8:9], exec
	v_mbcnt_lo_u32_b32 v1, s8, 0
	v_mbcnt_hi_u32_b32 v1, s9, v1
	s_waitcnt lgkmcnt(0)
	global_load_dword v0, v2, s[6:7] offset:40
	v_cmp_eq_u32_e32 vcc, 0, v1
	s_and_saveexec_b64 s[14:15], vcc
	s_cbranch_execz .LBB0_1755
	s_bcnt1_i32_b64 s8, s[8:9]
	v_mov_b32_e32 v3, s8
	global_atomic_add v3, v2, v3, s[6:7] offset:32 sc0

.LBB0_1874:
	s_or_b64 exec, exec, s[0:1]
	s_barrier
	v_readlane_b32 s1, v251, 2
	v_readfirstlane_b32 s0, v228
	s_ashr_i32 s0, s0, 6
	s_add_i32 s10, s0, s1
	s_cmp_gt_i32 s10, 0x100ff
	s_cbranch_scc1 .LBB0_1883
	v_and_b32_e32 v1, 63, v228
	v_mov_b32_e32 v0, 0
	v_lshlrev_b32_e32 v4, 3, v1
	v_mov_b32_e32 v5, v0
	v_lshlrev_b32_e32 v10, 4, v1
	v_mov_b32_e32 v11, v0
	v_cmp_gt_u32_e64 s[0:1], 16, v1
	v_lshl_add_u64 v[2:3], s[96:97], 0, v[4:5]
	v_lshl_add_u64 v[4:5], s[16:17], 0, v[4:5]
	v_lshl_add_u64 v[6:7], s[84:85], 0, v[10:11]
	v_lshl_add_u64 v[8:9], s[86:87], 0, v[10:11]
	v_lshl_add_u64 v[10:11], s[88:89], 0, v[10:11]
	s_mov_b32 s4, 0x3a800000
	s_mov_b32 s5, 0xf800000
	v_mov_b32_e32 v30, 0x260
	v_readfirstlane_b32 s8, v228
	s_cmpk_lt_u32 s8, 0x100
	s_cbranch_scc0 .Lln2prio_skip
	s_setprio 1
.Lln2prio_skip:
	global_load_dwordx4 v[60:63], v[6:7], off
	global_load_dwordx4 v[76:79], v[8:9], off
	global_load_dwordx4 v[64:67], v[6:7], off offset:1024
	global_load_dwordx4 v[80:83], v[8:9], off offset:1024
	global_load_dwordx4 v[68:71], v[6:7], off offset:2048
	global_load_dwordx4 v[84:87], v[8:9], off offset:2048
	global_load_dwordx4 v[72:75], v[6:7], off offset:3072
	global_load_dwordx4 v[88:91], v[8:9], off offset:3072
	v_mov_b32_e32 v170, 0
	v_mov_b32_e32 v171, 0
	v_mov_b32_e32 v172, 0
	v_mov_b32_e32 v173, 0
	s_add_i32 s14, s10, s76
	s_cmp_lt_i32 s14, 0x10100
	s_cselect_b32 s14, s14, s10
	s_ashr_i32 s11, s10, 31
	s_ashr_i32 s15, s14, 31
	s_lshl_b64 s[8:9], s[10:11], 11
	v_lshl_add_u64 v[174:175], v[2:3], 0, s[8:9]
	s_lshl_b64 s[8:9], s[14:15], 11
	v_lshl_add_u64 v[176:177], v[2:3], 0, s[8:9]
	s_lshl_b64 s[8:9], s[10:11], 7
	v_lshl_add_u64 v[178:179], v[4:5], 0, s[8:9]
	s_lshl_b64 s[8:9], s[14:15], 7
	v_lshl_add_u64 v[180:181], v[4:5], 0, s[8:9]
	s_and_saveexec_b64 s[8:9], s[0:1]
	global_load_dwordx2 v[170:171], v[178:179], off
	global_load_dwordx2 v[172:173], v[180:181], off
	s_mov_b64 exec, s[8:9]
	global_load_dwordx2 v[100:101], v[174:175], off nt
	global_load_dwordx2 v[102:103], v[174:175], off offset:512 nt
	global_load_dwordx2 v[104:105], v[174:175], off offset:1024 nt
	global_load_dwordx2 v[106:107], v[174:175], off offset:1536 nt
	global_load_dwordx2 v[108:109], v[176:177], off nt
	global_load_dwordx2 v[110:111], v[176:177], off offset:512 nt
	global_load_dwordx2 v[112:113], v[176:177], off offset:1024 nt
	global_load_dwordx2 v[114:115], v[176:177], off offset:1536 nt
	s_waitcnt vmcnt(0)
